# v35: v30 + split grid barriers: waiters poll the top-level arrival counter (>= (gen+1)*nx) instead of the generation word bumped after the counter atomic returns (release visible one round trip earlie
# baseline (speedup 1.0000x reference)
; DEV int opaque_tid() { int t = threadIdx.x; asm volatile("" : "+v"(t)); return t; }
; #define LAS __attribute__((address_space(3)))
; DEV unsigned xb_ld(unsigned* p) { return __hip_atomic_load(p, __ATOMIC_RELAXED, __HIP_MEMORY_SCOPE_AGENT); }
; DEV unsigned xb_add(unsigned* p, unsigned v) { return __hip_atomic_fetch_add(p, v, __ATOMIC_RELAXED, __HIP_MEMORY_SCOPE_AGENT); }
; DEV unsigned xb_xcc_id() { return (unsigned)__builtin_amdgcn_s_getreg((3 << 11) | 20) & 0xFu; }
; #define XB_SPIN(cond, bar) do { unsigned _sp = 0; while (cond) { __builtin_amdgcn_s_sleep(1); \
;     if ((++_sp & 255u) == 0u) { if (xb_ld(&(bar)[XB_TMO])) break; if (_sp > XB_SPIN_CAP) { atomicAdd(&(bar)[XB_TMO], 1u); break; } } } } while (0)
; DEV void xcd_wait_lds(LAS char* lds) {
;     volatile LAS unsigned* st = (volatile LAS unsigned*)(lds + LDS_BYTES - 16);
;     const int tid_ = opaque_tid();
;     if (tid_ == 64) asm volatile("buffer_inv sc1\n\ts_waitcnt vmcnt(0)" ::: "memory");
;     if (tid_ == 0) {
;         unsigned* bar = (unsigned*)((char*)ldptr(lds, 30) + SLOTS * 7 + BAR_OFF);
;         const unsigned x = xb_xcc_id();
;         const unsigned mode = st[2], val = st[3];
;         if (mode != 3u) XB_SPIN(xb_ld(&bar[XB_TOPGEN]) <= val, bar);
;         if (mode == 2u) xb_add(&bar[XB_XGEN(x)], 1u);
;         asm volatile("s_waitcnt vmcnt(0)" ::: "memory");
.LBB0_180:
	s_or_b64 exec, exec, s[0:1]
	v_cmp_eq_u32_e64 s[0:1], 0, v2
	s_and_saveexec_b64 s[4:5], s[0:1]
	s_cbranch_execz .LBB0_200
	s_add_i32 s2, 0, 0x24ef0
	v_mov_b32_e32 v0, s2
	s_add_i32 s2, 0, 0x24ef4
	s_add_i32 s6, 0, 0x24ff8
	v_mov_b32_e32 v1, s2
	v_mov_b32_e32 v2, s6
	ds_read_b32 v0, v0
	ds_read_b32 v1, v1
	s_getreg_b32 s2, hwreg(HW_REG_XCC_ID, 0, 4)
	ds_read_b32 v2, v2
	s_add_i32 s6, 0, 0x24ffc
	v_mov_b32_e32 v3, s6
	ds_read_b32 v3, v3
	v_mov_b32_e32 v4, 0x24ff4
	ds_read_b32 v4, v4
	s_waitcnt lgkmcnt(3)
	v_readfirstlane_b32 s6, v0
	s_waitcnt lgkmcnt(1)
	v_cmp_eq_u32_e32 vcc, 3, v2
	v_readfirstlane_b32 s7, v1
	s_cbranch_vccnz .LBB0_199
	v_mov_b32_e32 v0, 0xf781000
	s_nop 2
	global_load_dword v0, v0, s[6:7] offset:1024 sc1
	s_add_u32 s10, s6, 0xf781400
	s_addc_u32 s11, s7, 0
	s_waitcnt vmcnt(0) lgkmcnt(0)
	v_add_u32_e32 v3, 1, v3
	v_mul_lo_u32 v3, v3, v4
	v_add_u32_e32 v3, -1, v3
	v_cmp_gt_u32_e32 vcc, v0, v3
	s_cbranch_vccnz .LBB0_195
	s_add_u32 s8, s6, 0xf77e200
	s_addc_u32 s9, s7, 0
	s_mov_b32 s18, 1
	v_mov_b32_e32 v4, 0
	s_branch .LBB0_185

; DEV int opaque_tid() { int t = threadIdx.x; asm volatile("" : "+v"(t)); return t; }
; #define LAS __attribute__((address_space(3)))
; DEV unsigned xb_ld(unsigned* p) { return __hip_atomic_load(p, __ATOMIC_RELAXED, __HIP_MEMORY_SCOPE_AGENT); }
; DEV unsigned xb_add(unsigned* p, unsigned v) { return __hip_atomic_fetch_add(p, v, __ATOMIC_RELAXED, __HIP_MEMORY_SCOPE_AGENT); }
; DEV unsigned xb_xcc_id() { return (unsigned)__builtin_amdgcn_s_getreg((3 << 11) | 20) & 0xFu; }
; #define XB_SPIN(cond, bar) do { unsigned _sp = 0; while (cond) { __builtin_amdgcn_s_sleep(1); \
;     if ((++_sp & 255u) == 0u) { if (xb_ld(&(bar)[XB_TMO])) break; if (_sp > XB_SPIN_CAP) { atomicAdd(&(bar)[XB_TMO], 1u); break; } } } } while (0)
; DEV void xcd_wait_lds(LAS char* lds) {
;     volatile LAS unsigned* st = (volatile LAS unsigned*)(lds + LDS_BYTES - 16);
;     const int tid_ = opaque_tid();
;     if (tid_ == 64) asm volatile("buffer_inv sc1\n\ts_waitcnt vmcnt(0)" ::: "memory");
;     if (tid_ == 0) {
;         unsigned* bar = (unsigned*)((char*)ldptr(lds, 30) + SLOTS * 7 + BAR_OFF);
;         const unsigned x = xb_xcc_id();
;         const unsigned mode = st[2], val = st[3];
;         if (mode != 3u) XB_SPIN(xb_ld(&bar[XB_TOPGEN]) <= val, bar);
;         if (mode == 2u) xb_add(&bar[XB_XGEN(x)], 1u);
;         asm volatile("s_waitcnt vmcnt(0)" ::: "memory");
.LBB0_430:
	s_or_b64 exec, exec, s[0:1]
	v_cmp_eq_u32_e64 s[4:5], 0, v2
	s_and_saveexec_b64 s[6:7], s[4:5]
	s_cbranch_execz .LBB0_450
	s_add_i32 s0, 0, 0x24ef0
	v_mov_b32_e32 v0, s0
	s_add_i32 s0, 0, 0x24ef4
	v_mov_b32_e32 v1, s0
	s_add_i32 s0, 0, 0x24ff8
	v_mov_b32_e32 v2, s0
	ds_read_b32 v0, v0
	ds_read_b32 v1, v1
	s_getreg_b32 s2, hwreg(HW_REG_XCC_ID, 0, 4)
	ds_read_b32 v2, v2
	s_add_i32 s0, 0, 0x24ffc
	v_mov_b32_e32 v3, s0
	ds_read_b32 v3, v3
	v_mov_b32_e32 v4, 0x24ff4
	ds_read_b32 v4, v4
	s_waitcnt lgkmcnt(3)
	v_readfirstlane_b32 s8, v0
	s_waitcnt lgkmcnt(1)
	v_cmp_eq_u32_e32 vcc, 3, v2
	v_readfirstlane_b32 s9, v1
	s_cbranch_vccnz .LBB0_449
	v_mov_b32_e32 v0, 0xf781000
	s_nop 2
	global_load_dword v0, v0, s[8:9] offset:1024 sc1
	s_add_u32 s10, s8, 0xf781400
	s_addc_u32 s11, s9, 0
	s_waitcnt vmcnt(0) lgkmcnt(0)
	v_add_u32_e32 v3, 1, v3
	v_mul_lo_u32 v3, v3, v4
	v_add_u32_e32 v3, -1, v3
	v_cmp_gt_u32_e32 vcc, v0, v3
	s_cbranch_vccnz .LBB0_445
	s_add_u32 s0, s8, 0xf77e200
	s_addc_u32 s1, s9, 0
	s_mov_b32 s18, 1
	v_mov_b32_e32 v4, 0
	s_branch .LBB0_435

; DEV unsigned xb_ld(unsigned* p) { return __hip_atomic_load(p, __ATOMIC_RELAXED, __HIP_MEMORY_SCOPE_AGENT); }
; DEV unsigned xb_add(unsigned* p, unsigned v) { return __hip_atomic_fetch_add(p, v, __ATOMIC_RELAXED, __HIP_MEMORY_SCOPE_AGENT); }
; DEV unsigned xb_xcc_id() { return (unsigned)__builtin_amdgcn_s_getreg((3 << 11) | 20) & 0xFu; }
; #define XB_SPIN(cond, bar) do { unsigned _sp = 0; while (cond) { __builtin_amdgcn_s_sleep(1); \
;     if ((++_sp & 255u) == 0u) { if (xb_ld(&(bar)[XB_TMO])) break; if (_sp > XB_SPIN_CAP) { atomicAdd(&(bar)[XB_TMO], 1u); break; } } } } while (0)
; DEV void xcd_wait_lds(LAS char* lds) {
;     ...
;     if (tid_ == 0) {
;         unsigned* bar = (unsigned*)((char*)ldptr(lds, 30) + SLOTS * 7 + BAR_OFF);
;         const unsigned x = xb_xcc_id();
;         const unsigned mode = st[2], val = st[3];
;         if (mode != 3u) XB_SPIN(xb_ld(&bar[XB_TOPGEN]) <= val, bar);
;         if (mode == 2u) xb_add(&bar[XB_XGEN(x)], 1u);
;         asm volatile("s_waitcnt vmcnt(0)" ::: "memory");
.LBB0_720:
	s_or_b64 exec, exec, s[0:1]
	v_cmp_eq_u32_e64 s[8:9], 0, v131
	s_and_saveexec_b64 s[42:43], s[8:9]
	s_cbranch_execz .LBB0_740
	v_mov_b32_e32 v0, s69
	v_mov_b32_e32 v1, s56
	v_mov_b32_e32 v131, s68
	ds_read_b32 v0, v0
	ds_read_b32 v1, v1
	s_getreg_b32 s26, hwreg(HW_REG_XCC_ID, 0, 4)
	ds_read_b32 v131, v131
	v_mov_b32_e32 v132, s57
	ds_read_b32 v132, v132
	s_waitcnt lgkmcnt(0)
	v_readfirstlane_b32 s80, v0
	v_readfirstlane_b32 s81, v1
	v_mov_b32_e32 v1, 0x24ff4
	ds_read_b32 v1, v1
	v_cmp_eq_u32_e32 vcc, 3, v131
	s_cbranch_vccnz .LBB0_739
	s_nop 2
	global_load_dword v0, v209, s[80:81] offset:1024 sc1
	s_add_u32 s82, s80, 0xf781400
	s_addc_u32 s83, s81, 0
	s_waitcnt vmcnt(0) lgkmcnt(0)
	v_add_u32_e32 v132, 1, v132
	v_mul_lo_u32 v132, v132, v1
	v_add_u32_e32 v132, -1, v132
	v_cmp_gt_u32_e32 vcc, v0, v132
	s_cbranch_vccnz .LBB0_735
	s_add_u32 s0, s80, 0xf77e200
	s_addc_u32 s1, s81, 0
	s_mov_b32 s31, 1
	s_branch .LBB0_725

; DEV unsigned xb_ld(unsigned* p) { return __hip_atomic_load(p, __ATOMIC_RELAXED, __HIP_MEMORY_SCOPE_AGENT); }
; DEV unsigned xb_add(unsigned* p, unsigned v) { return __hip_atomic_fetch_add(p, v, __ATOMIC_RELAXED, __HIP_MEMORY_SCOPE_AGENT); }
; DEV unsigned xb_xcc_id() { return (unsigned)__builtin_amdgcn_s_getreg((3 << 11) | 20) & 0xFu; }
; #define XB_SPIN(cond, bar) do { unsigned _sp = 0; while (cond) { __builtin_amdgcn_s_sleep(1); \
;     if ((++_sp & 255u) == 0u) { if (xb_ld(&(bar)[XB_TMO])) break; if (_sp > XB_SPIN_CAP) { atomicAdd(&(bar)[XB_TMO], 1u); break; } } } } while (0)
; DEV void xcd_wait_lds(LAS char* lds) {
;     ...
;     if (tid_ == 0) {
;         unsigned* bar = (unsigned*)((char*)ldptr(lds, 30) + SLOTS * 7 + BAR_OFF);
;         const unsigned x = xb_xcc_id();
;         const unsigned mode = st[2], val = st[3];
;         if (mode != 3u) XB_SPIN(xb_ld(&bar[XB_TOPGEN]) <= val, bar);
;         if (mode == 2u) xb_add(&bar[XB_XGEN(x)], 1u);
;         asm volatile("s_waitcnt vmcnt(0)" ::: "memory");
.LBB0_1571:
	s_or_b64 exec, exec, s[6:7]
	v_cmp_eq_u32_e64 s[6:7], 0, v142
	s_and_saveexec_b64 s[40:41], s[6:7]
	s_cbranch_execz .LBB0_1591
	v_mov_b32_e32 v0, s83
	v_mov_b32_e32 v1, s84
	v_mov_b32_e32 v142, s82
	ds_read_b32 v0, v0
	ds_read_b32 v1, v1
	s_getreg_b32 s24, hwreg(HW_REG_XCC_ID, 0, 4)
	ds_read_b32 v142, v142
	v_mov_b32_e32 v143, s85
	ds_read_b32 v143, v143
	s_waitcnt lgkmcnt(0)
	v_readfirstlane_b32 s42, v0
	v_readfirstlane_b32 s43, v1
	v_mov_b32_e32 v1, 0x24ff4
	ds_read_b32 v1, v1
	v_cmp_eq_u32_e32 vcc, 3, v142
	s_cbranch_vccnz .LBB0_1590
	s_nop 2
	global_load_dword v0, v209, s[42:43] offset:1024 sc1
	s_add_u32 s64, s42, 0xf781400
	s_addc_u32 s65, s43, 0
	s_waitcnt vmcnt(0) lgkmcnt(0)
	v_add_u32_e32 v143, 1, v143
	v_mul_lo_u32 v143, v143, v1
	v_add_u32_e32 v143, -1, v143
	v_cmp_gt_u32_e32 vcc, v0, v143
	s_cbranch_vccnz .LBB0_1586
	s_add_u32 s56, s42, 0xf77e200
	s_mov_b32 s58, s70
	s_mov_b32 s54, s68
	s_addc_u32 s57, s43, 0
	s_mov_b32 s31, 1
	s_branch .LBB0_1576
